# last layer FFN2 epilogue: skip the bf16 residual-copy stores that nothing reads after the final sub-block
# speedup vs baseline: 1.0092x; 1.0016x over previous
.LBB0_2969:
	v_lshl_or_b32 v138, s42, 8, v160
	v_lshl_add_u32 v140, s48, 8, v158
	v_ashrrev_i32_e32 v139, 31, v138
	v_ashrrev_i32_e32 v141, 31, v140
	v_lshlrev_b64 v[142:143], 10, v[140:141]
	v_readlane_b32 s4, v254, 6
	v_lshl_add_u64 v[142:143], v[142:143], 0, v[138:139]
	v_readlane_b32 s5, v254, 7
	v_readlane_b32 s6, v254, 58
	v_readlane_b32 s7, v254, 59
	v_lshl_add_u64 v[154:155], v[142:143], 1, s[4:5]
	v_mov_b32_e32 v234, v140
	v_ashrrev_i32_e32 v235, 31, v234
	v_lshlrev_b64 v[234:235], 11, v[234:235]
	v_lshl_add_u64 v[234:235], s[4:5], 0, v[234:235]
	v_lshl_add_u64 v[234:235], v[138:139], 1, v[234:235]
	global_load_dwordx4 v[186:189], v[234:235], off
	global_load_dwordx4 v[190:193], v[234:235], off offset:256
	v_add_u32_e32 v234, 16, v140
	v_ashrrev_i32_e32 v235, 31, v234
	v_lshlrev_b64 v[234:235], 11, v[234:235]
	v_lshl_add_u64 v[234:235], s[4:5], 0, v[234:235]
	v_lshl_add_u64 v[234:235], v[138:139], 1, v[234:235]
	global_load_dwordx4 v[194:197], v[234:235], off
	global_load_dwordx4 v[198:201], v[234:235], off offset:256
	v_add_u32_e32 v234, 32, v140
	v_ashrrev_i32_e32 v235, 31, v234
	v_lshlrev_b64 v[234:235], 11, v[234:235]
	v_lshl_add_u64 v[234:235], s[4:5], 0, v[234:235]
	v_lshl_add_u64 v[234:235], v[138:139], 1, v[234:235]
	global_load_dwordx4 v[202:205], v[234:235], off
	global_load_dwordx4 v[206:209], v[234:235], off offset:256
	v_add_u32_e32 v234, 48, v140
	v_ashrrev_i32_e32 v235, 31, v234
	v_lshlrev_b64 v[234:235], 11, v[234:235]
	v_lshl_add_u64 v[234:235], s[4:5], 0, v[234:235]
	v_lshl_add_u64 v[234:235], v[138:139], 1, v[234:235]
	global_load_dwordx4 v[210:213], v[234:235], off
	global_load_dwordx4 v[214:217], v[234:235], off offset:256
	v_add_u32_e32 v234, 128, v140
	v_ashrrev_i32_e32 v235, 31, v234
	v_lshlrev_b64 v[234:235], 11, v[234:235]
	v_lshl_add_u64 v[234:235], s[4:5], 0, v[234:235]
	v_lshl_add_u64 v[234:235], v[138:139], 1, v[234:235]
	global_load_dwordx4 v[218:221], v[234:235], off
	global_load_dwordx4 v[222:225], v[234:235], off offset:256
	v_add_u32_e32 v234, 144, v140
	v_ashrrev_i32_e32 v235, 31, v234
	v_lshlrev_b64 v[234:235], 11, v[234:235]
	v_lshl_add_u64 v[234:235], s[4:5], 0, v[234:235]
	v_lshl_add_u64 v[234:235], v[138:139], 1, v[234:235]
	global_load_dwordx4 v[226:229], v[234:235], off
	global_load_dwordx4 v[230:233], v[234:235], off offset:256
	s_waitcnt vmcnt(0)
	s_andn2_b64 vcc, exec, s[10:11]
	s_waitcnt lgkmcnt(0)
	v_lshlrev_b32_e32 v166, 16, v186
	v_and_b32_e32 v167, 0xffff0000, v186
	v_lshlrev_b32_e32 v162, 16, v187
	v_and_b32_e32 v163, 0xffff0000, v187
	v_pk_add_f32 v[126:127], v[126:127], v[162:163]
	v_lshlrev_b32_e32 v162, 16, v188
	v_and_b32_e32 v163, 0xffff0000, v188
	v_pk_add_f32 v[120:121], v[120:121], v[162:163]
	v_lshlrev_b32_e32 v162, 16, v189
	v_and_b32_e32 v163, 0xffff0000, v189
	v_pk_add_f32 v[122:123], v[122:123], v[162:163]
	v_cndmask_b32_e64 v162, 0, 1, s[10:11]
	v_cmp_ne_u32_e64 s[4:5], 1, v162
	v_cndmask_b32_e64 v162, 0, 1, s[6:7]
	v_pk_add_f32 v[124:125], v[124:125], v[166:167]
	v_cmp_ne_u32_e64 s[6:7], 1, v162
	s_cbranch_vccnz .LBB0_2973
	s_and_b64 vcc, exec, s[6:7]
	s_cbranch_vccnz .LBB0_2972
	v_lshl_add_u64 v[162:163], v[142:143], 2, s[44:45]
	global_store_dwordx4 v[162:163], v[124:127], off
	global_store_dwordx4 v[162:163], v[120:123], off offset:16
	s_nop 1
	s_branch .LBB0_2973

.LBB0_2973:
	v_lshlrev_b64 v[154:155], 1, v[142:143]
	v_readlane_b32 s46, v254, 6
	v_or_b32_e32 v154, 0x100, v154
	v_readlane_b32 s47, v254, 7
	s_and_b64 vcc, exec, s[4:5]
	s_nop 0
	v_lshl_add_u64 v[154:155], s[46:47], 0, v[154:155]
	s_waitcnt lgkmcnt(0)
	v_lshlrev_b32_e32 v166, 16, v190
	v_and_b32_e32 v167, 0xffff0000, v190
	v_lshlrev_b32_e32 v162, 16, v191
	v_and_b32_e32 v163, 0xffff0000, v191
	v_pk_add_f32 v[118:119], v[118:119], v[162:163]
	v_lshlrev_b32_e32 v162, 16, v192
	v_and_b32_e32 v163, 0xffff0000, v192
	v_pk_add_f32 v[112:113], v[112:113], v[162:163]
	v_lshlrev_b32_e32 v162, 16, v193
	v_and_b32_e32 v163, 0xffff0000, v193
	v_pk_add_f32 v[116:117], v[116:117], v[166:167]
	v_pk_add_f32 v[114:115], v[114:115], v[162:163]
	s_cbranch_vccnz .LBB0_2977
	s_and_b64 vcc, exec, s[6:7]
	s_cbranch_vccnz .LBB0_2976
	v_lshl_add_u64 v[142:143], v[142:143], 2, s[44:45]
	global_store_dwordx4 v[142:143], v[116:119], off offset:512
	global_store_dwordx4 v[142:143], v[112:115], off offset:528
	s_nop 1
	s_branch .LBB0_2977

.LBB0_2979:
	s_or_b64 exec, exec, s[46:47]
	v_or_b32_e32 v112, 16, v140
	s_waitcnt lgkmcnt(0)
	v_ashrrev_i32_e32 v113, 31, v112
	v_lshlrev_b64 v[114:115], 10, v[112:113]
	v_readlane_b32 s46, v254, 6
	v_lshl_add_u64 v[114:115], v[114:115], 0, v[138:139]
	v_readlane_b32 s47, v254, 7
	s_and_b64 vcc, exec, s[4:5]
	s_nop 0
	v_lshl_add_u64 v[116:117], v[114:115], 1, s[46:47]
	s_waitcnt lgkmcnt(0)
	v_lshlrev_b32_e32 v122, 16, v194
	v_and_b32_e32 v123, 0xffff0000, v194
	v_lshlrev_b32_e32 v118, 16, v195
	v_and_b32_e32 v119, 0xffff0000, v195
	v_pk_add_f32 v[110:111], v[110:111], v[118:119]
	v_lshlrev_b32_e32 v118, 16, v196
	v_and_b32_e32 v119, 0xffff0000, v196
	v_pk_add_f32 v[104:105], v[104:105], v[118:119]
	v_lshlrev_b32_e32 v118, 16, v197
	v_and_b32_e32 v119, 0xffff0000, v197
	v_pk_add_f32 v[108:109], v[108:109], v[122:123]
	v_pk_add_f32 v[106:107], v[106:107], v[118:119]
	s_cbranch_vccnz .LBB0_2983
	s_and_b64 vcc, exec, s[6:7]
	s_cbranch_vccnz .LBB0_2982
	v_lshl_add_u64 v[118:119], v[114:115], 2, s[44:45]
	global_store_dwordx4 v[118:119], v[108:111], off
	global_store_dwordx4 v[118:119], v[104:107], off offset:16
	s_nop 1
	s_branch .LBB0_2983

.LBB0_2983:
	v_lshlrev_b64 v[116:117], 1, v[114:115]
	v_readlane_b32 s46, v254, 6
	v_or_b32_e32 v116, 0x100, v116
	v_readlane_b32 s47, v254, 7
	s_and_b64 vcc, exec, s[4:5]
	s_nop 0
	v_lshl_add_u64 v[116:117], s[46:47], 0, v[116:117]
	s_waitcnt lgkmcnt(0)
	v_lshlrev_b32_e32 v122, 16, v198
	v_and_b32_e32 v123, 0xffff0000, v198
	v_lshlrev_b32_e32 v118, 16, v199
	v_and_b32_e32 v119, 0xffff0000, v199
	v_pk_add_f32 v[102:103], v[102:103], v[118:119]
	v_lshlrev_b32_e32 v118, 16, v200
	v_and_b32_e32 v119, 0xffff0000, v200
	v_pk_add_f32 v[96:97], v[96:97], v[118:119]
	v_lshlrev_b32_e32 v118, 16, v201
	v_and_b32_e32 v119, 0xffff0000, v201
	v_pk_add_f32 v[100:101], v[100:101], v[122:123]
	v_pk_add_f32 v[98:99], v[98:99], v[118:119]
	s_cbranch_vccnz .LBB0_2987
	s_and_b64 vcc, exec, s[6:7]
	s_cbranch_vccnz .LBB0_2986
	v_lshl_add_u64 v[114:115], v[114:115], 2, s[44:45]
	global_store_dwordx4 v[114:115], v[100:103], off offset:512
	global_store_dwordx4 v[114:115], v[96:99], off offset:528
	s_nop 1
	s_branch .LBB0_2987

.LBB0_2989:
	s_or_b64 exec, exec, s[46:47]
	v_or_b32_e32 v96, 32, v140
	s_waitcnt lgkmcnt(0)
	v_ashrrev_i32_e32 v97, 31, v96
	v_lshlrev_b64 v[98:99], 10, v[96:97]
	v_readlane_b32 s46, v254, 6
	v_lshl_add_u64 v[98:99], v[98:99], 0, v[138:139]
	v_readlane_b32 s47, v254, 7
	s_and_b64 vcc, exec, s[4:5]
	s_nop 0
	v_lshl_add_u64 v[100:101], v[98:99], 1, s[46:47]
	s_waitcnt lgkmcnt(0)
	v_lshlrev_b32_e32 v106, 16, v202
	v_and_b32_e32 v107, 0xffff0000, v202
	v_lshlrev_b32_e32 v102, 16, v203
	v_and_b32_e32 v103, 0xffff0000, v203
	v_pk_add_f32 v[94:95], v[94:95], v[102:103]
	v_lshlrev_b32_e32 v102, 16, v204
	v_and_b32_e32 v103, 0xffff0000, v204
	v_pk_add_f32 v[88:89], v[88:89], v[102:103]
	v_lshlrev_b32_e32 v102, 16, v205
	v_and_b32_e32 v103, 0xffff0000, v205
	v_pk_add_f32 v[92:93], v[92:93], v[106:107]
	v_pk_add_f32 v[90:91], v[90:91], v[102:103]
	s_cbranch_vccnz .LBB0_2993
	s_and_b64 vcc, exec, s[6:7]
	s_cbranch_vccnz .LBB0_2992
	v_lshl_add_u64 v[102:103], v[98:99], 2, s[44:45]
	global_store_dwordx4 v[102:103], v[92:95], off
	global_store_dwordx4 v[102:103], v[88:91], off offset:16
	s_nop 1
	s_branch .LBB0_2993

.LBB0_2993:
	v_lshlrev_b64 v[100:101], 1, v[98:99]
	v_readlane_b32 s46, v254, 6
	v_or_b32_e32 v100, 0x100, v100
	v_readlane_b32 s47, v254, 7
	s_and_b64 vcc, exec, s[4:5]
	s_nop 0
	v_lshl_add_u64 v[100:101], s[46:47], 0, v[100:101]
	s_waitcnt lgkmcnt(0)
	v_lshlrev_b32_e32 v106, 16, v206
	v_and_b32_e32 v107, 0xffff0000, v206
	v_lshlrev_b32_e32 v102, 16, v207
	v_and_b32_e32 v103, 0xffff0000, v207
	v_pk_add_f32 v[86:87], v[86:87], v[102:103]
	v_lshlrev_b32_e32 v102, 16, v208
	v_and_b32_e32 v103, 0xffff0000, v208
	v_pk_add_f32 v[80:81], v[80:81], v[102:103]
	v_lshlrev_b32_e32 v102, 16, v209
	v_and_b32_e32 v103, 0xffff0000, v209
	v_pk_add_f32 v[84:85], v[84:85], v[106:107]
	v_pk_add_f32 v[82:83], v[82:83], v[102:103]
	s_cbranch_vccnz .LBB0_2997
	s_and_b64 vcc, exec, s[6:7]
	s_cbranch_vccnz .LBB0_2996
	v_lshl_add_u64 v[98:99], v[98:99], 2, s[44:45]
	global_store_dwordx4 v[98:99], v[84:87], off offset:512
	global_store_dwordx4 v[98:99], v[80:83], off offset:528
	s_nop 1
	s_branch .LBB0_2997

.LBB0_2999:
	s_or_b64 exec, exec, s[46:47]
	v_or_b32_e32 v80, 48, v140
	s_waitcnt lgkmcnt(0)
	v_ashrrev_i32_e32 v81, 31, v80
	v_lshlrev_b64 v[82:83], 10, v[80:81]
	v_readlane_b32 s46, v254, 6
	v_lshl_add_u64 v[82:83], v[82:83], 0, v[138:139]
	v_readlane_b32 s47, v254, 7
	s_and_b64 vcc, exec, s[4:5]
	s_nop 0
	v_lshl_add_u64 v[84:85], v[82:83], 1, s[46:47]
	s_waitcnt lgkmcnt(0)
	v_lshlrev_b32_e32 v90, 16, v210
	v_and_b32_e32 v91, 0xffff0000, v210
	v_lshlrev_b32_e32 v86, 16, v211
	v_and_b32_e32 v87, 0xffff0000, v211
	v_pk_add_f32 v[78:79], v[78:79], v[86:87]
	v_lshlrev_b32_e32 v86, 16, v212
	v_and_b32_e32 v87, 0xffff0000, v212
	v_pk_add_f32 v[72:73], v[72:73], v[86:87]
	v_lshlrev_b32_e32 v86, 16, v213
	v_and_b32_e32 v87, 0xffff0000, v213
	v_pk_add_f32 v[76:77], v[76:77], v[90:91]
	v_pk_add_f32 v[74:75], v[74:75], v[86:87]
	s_cbranch_vccnz .LBB0_3003
	s_and_b64 vcc, exec, s[6:7]
	s_cbranch_vccnz .LBB0_3002
	v_lshl_add_u64 v[86:87], v[82:83], 2, s[44:45]
	global_store_dwordx4 v[86:87], v[76:79], off
	global_store_dwordx4 v[86:87], v[72:75], off offset:16
	s_nop 1
	s_branch .LBB0_3003

.LBB0_3003:
	v_lshlrev_b64 v[84:85], 1, v[82:83]
	v_readlane_b32 s46, v254, 6
	v_or_b32_e32 v84, 0x100, v84
	v_readlane_b32 s47, v254, 7
	s_and_b64 vcc, exec, s[4:5]
	s_nop 0
	v_lshl_add_u64 v[84:85], s[46:47], 0, v[84:85]
	s_waitcnt lgkmcnt(0)
	v_lshlrev_b32_e32 v90, 16, v214
	v_and_b32_e32 v91, 0xffff0000, v214
	v_lshlrev_b32_e32 v86, 16, v215
	v_and_b32_e32 v87, 0xffff0000, v215
	v_pk_add_f32 v[70:71], v[70:71], v[86:87]
	v_lshlrev_b32_e32 v86, 16, v216
	v_and_b32_e32 v87, 0xffff0000, v216
	v_pk_add_f32 v[64:65], v[64:65], v[86:87]
	v_lshlrev_b32_e32 v86, 16, v217
	v_and_b32_e32 v87, 0xffff0000, v217
	v_pk_add_f32 v[68:69], v[68:69], v[90:91]
	v_pk_add_f32 v[66:67], v[66:67], v[86:87]
	s_cbranch_vccnz .LBB0_3007
	s_and_b64 vcc, exec, s[6:7]
	s_cbranch_vccnz .LBB0_3006
	v_lshl_add_u64 v[82:83], v[82:83], 2, s[44:45]
	global_store_dwordx4 v[82:83], v[68:71], off offset:512
	global_store_dwordx4 v[82:83], v[64:67], off offset:528
	s_nop 1
	s_branch .LBB0_3007

.LBB0_3009:
	s_or_b64 exec, exec, s[46:47]
	v_add_u32_e32 v64, 0x80, v140
	s_waitcnt lgkmcnt(0)
	v_ashrrev_i32_e32 v65, 31, v64
	v_lshlrev_b64 v[66:67], 10, v[64:65]
	v_readlane_b32 s46, v254, 6
	v_lshl_add_u64 v[66:67], v[66:67], 0, v[138:139]
	v_readlane_b32 s47, v254, 7
	s_and_b64 vcc, exec, s[4:5]
	s_nop 0
	v_lshl_add_u64 v[68:69], v[66:67], 1, s[46:47]
	v_add_u32_e32 v234, 160, v140
	v_ashrrev_i32_e32 v235, 31, v234
	v_lshlrev_b64 v[234:235], 11, v[234:235]
	v_lshl_add_u64 v[234:235], s[46:47], 0, v[234:235]
	v_lshl_add_u64 v[234:235], v[138:139], 1, v[234:235]
	global_load_dwordx4 v[186:189], v[234:235], off
	global_load_dwordx4 v[190:193], v[234:235], off offset:256
	v_add_u32_e32 v234, 176, v140
	v_ashrrev_i32_e32 v235, 31, v234
	v_lshlrev_b64 v[234:235], 11, v[234:235]
	v_lshl_add_u64 v[234:235], s[46:47], 0, v[234:235]
	v_lshl_add_u64 v[234:235], v[138:139], 1, v[234:235]
	global_load_dwordx4 v[194:197], v[234:235], off
	global_load_dwordx4 v[198:201], v[234:235], off offset:256
	s_waitcnt lgkmcnt(0)
	v_lshlrev_b32_e32 v74, 16, v218
	v_and_b32_e32 v75, 0xffff0000, v218
	v_lshlrev_b32_e32 v70, 16, v219
	v_and_b32_e32 v71, 0xffff0000, v219
	v_pk_add_f32 v[62:63], v[62:63], v[70:71]
	v_lshlrev_b32_e32 v70, 16, v220
	v_and_b32_e32 v71, 0xffff0000, v220
	v_pk_add_f32 v[56:57], v[56:57], v[70:71]
	v_lshlrev_b32_e32 v70, 16, v221
	v_and_b32_e32 v71, 0xffff0000, v221
	v_pk_add_f32 v[60:61], v[60:61], v[74:75]
	v_pk_add_f32 v[58:59], v[58:59], v[70:71]
	s_cbranch_vccnz .LBB0_3013
	s_and_b64 vcc, exec, s[6:7]
	s_cbranch_vccnz .LBB0_3012
	v_lshl_add_u64 v[70:71], v[66:67], 2, s[44:45]
	global_store_dwordx4 v[70:71], v[60:63], off
	global_store_dwordx4 v[70:71], v[56:59], off offset:16
	s_nop 1
	s_branch .LBB0_3013

.LBB0_3013:
	v_lshlrev_b64 v[68:69], 1, v[66:67]
	v_readlane_b32 s46, v254, 6
	v_or_b32_e32 v68, 0x100, v68
	v_readlane_b32 s47, v254, 7
	s_and_b64 vcc, exec, s[4:5]
	s_nop 0
	v_lshl_add_u64 v[68:69], s[46:47], 0, v[68:69]
	s_waitcnt lgkmcnt(0)
	v_lshlrev_b32_e32 v74, 16, v222
	v_and_b32_e32 v75, 0xffff0000, v222
	v_lshlrev_b32_e32 v70, 16, v223
	v_and_b32_e32 v71, 0xffff0000, v223
	v_pk_add_f32 v[54:55], v[54:55], v[70:71]
	v_lshlrev_b32_e32 v70, 16, v224
	v_and_b32_e32 v71, 0xffff0000, v224
	v_pk_add_f32 v[48:49], v[48:49], v[70:71]
	v_lshlrev_b32_e32 v70, 16, v225
	v_and_b32_e32 v71, 0xffff0000, v225
	v_pk_add_f32 v[52:53], v[52:53], v[74:75]
	v_pk_add_f32 v[50:51], v[50:51], v[70:71]
	s_cbranch_vccnz .LBB0_3017
	s_and_b64 vcc, exec, s[6:7]
	s_cbranch_vccnz .LBB0_3016
	v_lshl_add_u64 v[66:67], v[66:67], 2, s[44:45]
	global_store_dwordx4 v[66:67], v[52:55], off offset:512
	global_store_dwordx4 v[66:67], v[48:51], off offset:528
	s_nop 1
	s_branch .LBB0_3017

.LBB0_3019:
	s_or_b64 exec, exec, s[46:47]
	v_add_u32_e32 v48, 0x90, v140
	s_waitcnt lgkmcnt(0)
	v_ashrrev_i32_e32 v49, 31, v48
	v_lshlrev_b64 v[50:51], 10, v[48:49]
	v_readlane_b32 s46, v254, 6
	v_lshl_add_u64 v[50:51], v[50:51], 0, v[138:139]
	v_readlane_b32 s47, v254, 7
	s_and_b64 vcc, exec, s[4:5]
	s_nop 0
	v_lshl_add_u64 v[52:53], v[50:51], 1, s[46:47]
	s_waitcnt lgkmcnt(0)
	v_lshlrev_b32_e32 v58, 16, v226
	v_and_b32_e32 v59, 0xffff0000, v226
	v_lshlrev_b32_e32 v54, 16, v227
	v_and_b32_e32 v55, 0xffff0000, v227
	v_pk_add_f32 v[46:47], v[46:47], v[54:55]
	v_lshlrev_b32_e32 v54, 16, v228
	v_and_b32_e32 v55, 0xffff0000, v228
	v_pk_add_f32 v[40:41], v[40:41], v[54:55]
	v_lshlrev_b32_e32 v54, 16, v229
	v_and_b32_e32 v55, 0xffff0000, v229
	v_pk_add_f32 v[44:45], v[44:45], v[58:59]
	v_pk_add_f32 v[42:43], v[42:43], v[54:55]
	s_cbranch_vccnz .LBB0_3023
	s_and_b64 vcc, exec, s[6:7]
	s_cbranch_vccnz .LBB0_3022
	v_lshl_add_u64 v[54:55], v[50:51], 2, s[44:45]
	global_store_dwordx4 v[54:55], v[44:47], off
	global_store_dwordx4 v[54:55], v[40:43], off offset:16
	s_nop 1
	s_branch .LBB0_3023

.LBB0_3023:
	v_lshlrev_b64 v[52:53], 1, v[50:51]
	v_readlane_b32 s46, v254, 6
	v_or_b32_e32 v52, 0x100, v52
	v_readlane_b32 s47, v254, 7
	s_and_b64 vcc, exec, s[4:5]
	s_nop 0
	v_lshl_add_u64 v[52:53], s[46:47], 0, v[52:53]
	s_waitcnt lgkmcnt(0)
	v_lshlrev_b32_e32 v58, 16, v230
	v_and_b32_e32 v59, 0xffff0000, v230
	v_lshlrev_b32_e32 v54, 16, v231
	v_and_b32_e32 v55, 0xffff0000, v231
	v_pk_add_f32 v[38:39], v[38:39], v[54:55]
	v_lshlrev_b32_e32 v54, 16, v232
	v_and_b32_e32 v55, 0xffff0000, v232
	v_pk_add_f32 v[32:33], v[32:33], v[54:55]
	v_lshlrev_b32_e32 v54, 16, v233
	v_and_b32_e32 v55, 0xffff0000, v233
	v_pk_add_f32 v[36:37], v[36:37], v[58:59]
	v_pk_add_f32 v[34:35], v[34:35], v[54:55]
	s_cbranch_vccnz .LBB0_3027
	s_and_b64 vcc, exec, s[6:7]
	s_cbranch_vccnz .LBB0_3026
	v_lshl_add_u64 v[50:51], v[50:51], 2, s[44:45]
	global_store_dwordx4 v[50:51], v[36:39], off offset:512
	global_store_dwordx4 v[50:51], v[32:35], off offset:528
	s_nop 1
	s_branch .LBB0_3027

.LBB0_3029:
	s_or_b64 exec, exec, s[46:47]
	v_add_u32_e32 v32, 0xa0, v140
	s_waitcnt lgkmcnt(0)
	v_ashrrev_i32_e32 v33, 31, v32
	v_lshlrev_b64 v[34:35], 10, v[32:33]
	v_readlane_b32 s46, v254, 6
	v_lshl_add_u64 v[34:35], v[34:35], 0, v[138:139]
	v_readlane_b32 s47, v254, 7
	s_and_b64 vcc, exec, s[4:5]
	s_nop 0
	v_lshl_add_u64 v[36:37], v[34:35], 1, s[46:47]
	s_waitcnt vmcnt(0)
	s_waitcnt lgkmcnt(0)
	v_lshlrev_b32_e32 v42, 16, v186
	v_and_b32_e32 v43, 0xffff0000, v186
	v_lshlrev_b32_e32 v38, 16, v187
	v_and_b32_e32 v39, 0xffff0000, v187
	v_pk_add_f32 v[30:31], v[30:31], v[38:39]
	v_lshlrev_b32_e32 v38, 16, v188
	v_and_b32_e32 v39, 0xffff0000, v188
	v_pk_add_f32 v[24:25], v[24:25], v[38:39]
	v_lshlrev_b32_e32 v38, 16, v189
	v_and_b32_e32 v39, 0xffff0000, v189
	v_pk_add_f32 v[28:29], v[28:29], v[42:43]
	v_pk_add_f32 v[26:27], v[26:27], v[38:39]
	s_cbranch_vccnz .LBB0_3033
	s_and_b64 vcc, exec, s[6:7]
	s_cbranch_vccnz .LBB0_3032
	v_lshl_add_u64 v[38:39], v[34:35], 2, s[44:45]
	global_store_dwordx4 v[38:39], v[28:31], off
	global_store_dwordx4 v[38:39], v[24:27], off offset:16
	s_nop 1
	s_branch .LBB0_3033

.LBB0_3033:
	v_lshlrev_b64 v[36:37], 1, v[34:35]
	v_readlane_b32 s46, v254, 6
	v_or_b32_e32 v36, 0x100, v36
	v_readlane_b32 s47, v254, 7
	s_and_b64 vcc, exec, s[4:5]
	s_nop 0
	v_lshl_add_u64 v[36:37], s[46:47], 0, v[36:37]
	s_waitcnt lgkmcnt(0)
	v_lshlrev_b32_e32 v42, 16, v190
	v_and_b32_e32 v43, 0xffff0000, v190
	v_lshlrev_b32_e32 v38, 16, v191
	v_and_b32_e32 v39, 0xffff0000, v191
	v_pk_add_f32 v[22:23], v[22:23], v[38:39]
	v_lshlrev_b32_e32 v38, 16, v192
	v_and_b32_e32 v39, 0xffff0000, v192
	v_pk_add_f32 v[16:17], v[16:17], v[38:39]
	v_lshlrev_b32_e32 v38, 16, v193
	v_and_b32_e32 v39, 0xffff0000, v193
	v_pk_add_f32 v[20:21], v[20:21], v[42:43]
	v_pk_add_f32 v[18:19], v[18:19], v[38:39]
	s_cbranch_vccnz .LBB0_3037
	s_and_b64 vcc, exec, s[6:7]
	s_cbranch_vccnz .LBB0_3036
	v_lshl_add_u64 v[34:35], v[34:35], 2, s[44:45]
	global_store_dwordx4 v[34:35], v[20:23], off offset:512
	global_store_dwordx4 v[34:35], v[16:19], off offset:528
	s_nop 1
	s_branch .LBB0_3037

.LBB0_3039:
	s_or_b64 exec, exec, s[46:47]
	v_add_u32_e32 v16, 0xb0, v140
	s_waitcnt lgkmcnt(0)
	v_ashrrev_i32_e32 v17, 31, v16
	v_lshlrev_b64 v[18:19], 10, v[16:17]
	v_readlane_b32 s46, v254, 6
	v_lshl_add_u64 v[18:19], v[18:19], 0, v[138:139]
	v_readlane_b32 s47, v254, 7
	s_and_b64 vcc, exec, s[4:5]
	s_nop 0
	v_lshl_add_u64 v[20:21], v[18:19], 1, s[46:47]
	s_waitcnt lgkmcnt(0)
	v_lshlrev_b32_e32 v26, 16, v194
	v_and_b32_e32 v27, 0xffff0000, v194
	v_lshlrev_b32_e32 v22, 16, v195
	v_and_b32_e32 v23, 0xffff0000, v195
	v_pk_add_f32 v[14:15], v[14:15], v[22:23]
	v_lshlrev_b32_e32 v22, 16, v196
	v_and_b32_e32 v23, 0xffff0000, v196
	v_pk_add_f32 v[8:9], v[8:9], v[22:23]
	v_lshlrev_b32_e32 v22, 16, v197
	v_and_b32_e32 v23, 0xffff0000, v197
	v_pk_add_f32 v[12:13], v[12:13], v[26:27]
	v_pk_add_f32 v[10:11], v[10:11], v[22:23]
	s_cbranch_vccnz .LBB0_3043
	s_and_b64 vcc, exec, s[6:7]
	s_cbranch_vccnz .LBB0_3042
	v_lshl_add_u64 v[22:23], v[18:19], 2, s[44:45]
	global_store_dwordx4 v[22:23], v[12:15], off
	global_store_dwordx4 v[22:23], v[8:11], off offset:16
	s_nop 1
	s_branch .LBB0_3043

.LBB0_3043:
	v_lshlrev_b64 v[20:21], 1, v[18:19]
	v_readlane_b32 s46, v254, 6
	v_or_b32_e32 v20, 0x100, v20
	v_readlane_b32 s47, v254, 7
	s_and_b64 vcc, exec, s[4:5]
	s_nop 0
	v_lshl_add_u64 v[20:21], s[46:47], 0, v[20:21]
	s_waitcnt lgkmcnt(0)
	v_lshlrev_b32_e32 v26, 16, v198
	v_and_b32_e32 v27, 0xffff0000, v198
	v_lshlrev_b32_e32 v22, 16, v199
	v_and_b32_e32 v23, 0xffff0000, v199
	v_pk_add_f32 v[6:7], v[6:7], v[22:23]
	v_lshlrev_b32_e32 v22, 16, v200
	v_and_b32_e32 v23, 0xffff0000, v200
	v_pk_add_f32 v[0:1], v[0:1], v[22:23]
	v_lshlrev_b32_e32 v22, 16, v201
	v_and_b32_e32 v23, 0xffff0000, v201
	v_pk_add_f32 v[4:5], v[4:5], v[26:27]
	v_pk_add_f32 v[2:3], v[2:3], v[22:23]
	s_cbranch_vccnz .LBB0_3047
	s_and_b64 vcc, exec, s[6:7]
	s_cbranch_vccnz .LBB0_3046
	v_lshl_add_u64 v[18:19], v[18:19], 2, s[44:45]
	global_store_dwordx4 v[18:19], v[4:7], off offset:512
	global_store_dwordx4 v[18:19], v[0:3], off offset:528
	s_nop 1
	s_branch .LBB0_3047
